# gla pass1 chunk loop tail: V^T image u16 reads and the decay-vector reads issued in batches (one wait each) instead of one read-wait pair at a time; both state MFMA pairs issued back to back
# speedup vs baseline: 1.0065x; 1.0029x over previous
.LBB0_533:
	s_or_b64 exec, exec, s[12:13]
	ds_read_u16 v113, v100 offset:55040
	ds_read_u16 v114, v100 offset:55296
	ds_read_u16 v115, v100 offset:55552
	ds_read_u16 v116, v100 offset:55808
	ds_read_u16 v117, v100 offset:56064
	ds_read_u16 v118, v100 offset:56320
	ds_read_u16 v119, v100 offset:56576
	ds_read_u16 v120, v100 offset:56832
	ds_read_u16 v121, v100 offset:57088
	ds_read_u16 v122, v100 offset:57344
	ds_read_u16 v123, v100 offset:57600
	ds_read_u16 v124, v100 offset:57856
	ds_read_u16 v125, v100 offset:58112
	ds_read_u16 v126, v100 offset:58368
	ds_read_u16 v127, v100 offset:58624
	ds_read_u16 v128, v100 offset:58880
	v_add_u32_e32 v112, s45, v90
	s_add_i32 s10, s10, -1
	s_add_i32 s54, s54, 1
	s_cmp_eq_u32 s10, -2
	s_waitcnt lgkmcnt(0)
	v_lshl_or_b32 v0, v114, 16, v113
	v_lshl_or_b32 v1, v116, 16, v115
	v_lshl_or_b32 v2, v118, 16, v117
	v_lshl_or_b32 v3, v120, 16, v119
	v_lshl_or_b32 v4, v122, 16, v121
	v_lshl_or_b32 v5, v124, 16, v123
	v_lshl_or_b32 v6, v126, 16, v125
	v_lshl_or_b32 v7, v128, 16, v127
	ds_write_b128 v101, v[0:3] offset:14336
	ds_write_b128 v101, v[4:7] offset:14352
	s_waitcnt lgkmcnt(0)
	s_barrier
	ds_read_b128 v[74:77], v102 offset:14336
	ds_read_b128 v[78:81], v102 offset:14368
	ds_read_b128 v[0:3], v103 offset:9216
	ds_read_b128 v[104:107], v103 offset:9248
	ds_read_b128 v[116:119], v103 offset:11776
	ds_read_b128 v[120:123], v103 offset:11808
	ds_read_b128 v[124:127], v112 offset:45568
	ds_read_b128 v[128:131], v112 offset:45600
	ds_read_b128 v[132:135], v112 offset:45632
	ds_read_b128 v[136:139], v112 offset:45664
	ds_read_b128 v[140:143], v112 offset:45696
	ds_read_b128 v[144:147], v112 offset:45728
	ds_read_b128 v[148:151], v112 offset:45760
	ds_read_b128 v[152:155], v112 offset:45792
	s_waitcnt lgkmcnt(11)
	v_mfma_f32_32x32x16_bf16 v[0:15], v[0:3], v[74:77], 0
	s_waitcnt lgkmcnt(10)
	v_mfma_f32_32x32x16_bf16 v[0:15], v[104:107], v[78:81], v[0:15]
	s_waitcnt lgkmcnt(9)
	v_mfma_f32_32x32x16_bf16 v[156:171], v[116:119], v[74:77], 0
	s_waitcnt lgkmcnt(8)
	v_mfma_f32_32x32x16_bf16 v[156:171], v[120:123], v[78:81], v[156:171]
	s_waitcnt lgkmcnt(0)
	s_nop 4
	v_pk_fma_f32 v[70:71], v[70:71], v[124:125], v[0:1]
	v_pk_fma_f32 v[68:69], v[68:69], v[126:127], v[2:3]
	v_pk_fma_f32 v[64:65], v[64:65], v[128:129], v[4:5]
	v_pk_fma_f32 v[62:63], v[62:63], v[130:131], v[6:7]
	v_pk_fma_f32 v[60:61], v[60:61], v[132:133], v[8:9]
	v_pk_fma_f32 v[58:59], v[58:59], v[134:135], v[10:11]
	v_pk_fma_f32 v[56:57], v[56:57], v[136:137], v[12:13]
	v_pk_fma_f32 v[52:53], v[52:53], v[138:139], v[14:15]
	s_nop 10
	v_pk_fma_f32 v[54:55], v[54:55], v[140:141], v[156:157]
	v_pk_fma_f32 v[50:51], v[50:51], v[142:143], v[158:159]
	v_pk_fma_f32 v[48:49], v[48:49], v[144:145], v[160:161]
	v_pk_fma_f32 v[46:47], v[46:47], v[146:147], v[162:163]
	v_pk_fma_f32 v[44:45], v[44:45], v[148:149], v[164:165]
	v_pk_fma_f32 v[40:41], v[40:41], v[150:151], v[166:167]
	v_pk_fma_f32 v[38:39], v[38:39], v[152:153], v[168:169]
	v_pk_fma_f32 v[36:37], v[36:37], v[154:155], v[170:171]
	s_cbranch_scc1 .LBB0_542
